# baseline (speedup 1.0000x reference)
; #define PG8_STAGE(bufoff, gbase, voff) do { _Pragma("unroll") for (int _i = 0; _i < 2; ++_i) \
;         __builtin_amdgcn_global_load_lds((const unsigned*)((const char*)(gbase) + (voff)[_i]), (LAS unsigned*)(lds + (bufoff) + ldsw + _i * 8192), 16, 0, 0); } while (0)
; #define PG8_LDA(dst, b, h) do { _Pragma("unroll") for (int m = 0; m < 4; ++m) _Pragma("unroll") for (int k = 0; k < 2; ++k) dst[m][k] = *(const LAS bf16x8*)(lds + PG8_SA(b, h) + aoff + m * 2048 + k * 1024); } while (0)
; #define PG8_LDB(dst, b, h) do { _Pragma("unroll") for (int n = 0; n < 2; ++n) _Pragma("unroll") for (int k = 0; k < 2; ++k) dst[n][k] = *(const LAS bf16x8*)(lds + PG8_SB(b, h) + boff + n * 2048 + k * 1024); } while (0)
; #define PG8_MMA(ai, bj, At, Bt) do { __builtin_amdgcn_s_setprio(1); _Pragma("unroll") for (int m = 0; m < 4; ++m) _Pragma("unroll") for (int n = 0; n < 2; ++n) _Pragma("unroll") for (int k = 0; k < 2; ++k) \
;         acc[ai][bj][m][n] = __builtin_amdgcn_mfma_f32_16x16x32_bf16(Bt[n][k], At[m][k], acc[ai][bj][m][n], 0, 0, 0); __builtin_amdgcn_s_setprio(0); } while (0)
; #define PG8_WAIT_V(n) asm volatile("s_waitcnt vmcnt(" #n ")" ::: "memory")
; #define PG8_WAIT_L(n) asm volatile("s_waitcnt lgkmcnt(" #n ")" ::: "memory")
; #define PG8_BAR __builtin_amdgcn_s_barrier()
; #define PG8_SCHED __builtin_amdgcn_sched_barrier(0)
; __device__ __forceinline__ void gemm_phase(LAS unsigned char* lds, const GemmD& g) {
;     ...
;             PG8_WAIT_L(8); PG8_BAR; PG8_WAIT_L(0); PG8_MMA(0, 0, At, B0); PG8_BAR; PG8_SCHED;
;             PG8_LDB(B1, 0, 1); PG8_STAGE(PG8_SB(0, 0), b2, voffB);
;             PG8_BAR; PG8_WAIT_L(0); PG8_MMA(0, 1, At, B1); PG8_BAR;
;             PG8_LDA(At, 0, 1); PG8_STAGE(PG8_SA(0, 0), a2, voffA);
;             PG8_BAR; PG8_WAIT_L(0); PG8_MMA(1, 0, At, B0); PG8_BAR; PG8_SCHED;
;             PG8_STAGE(PG8_SB(0, 1), b2 + hstep, voffB);
;             PG8_WAIT_V(6); PG8_BAR; PG8_MMA(1, 1, At, B1); PG8_BAR;
;             PG8_LDB(B0, 1, 0); PG8_SCHED; PG8_LDA(At, 1, 0); PG8_STAGE(PG8_SA(0, 1), a2 + hstep, voffA);
.Lkl_ptr_done:
	s_waitcnt lgkmcnt(8)
	s_barrier
	s_waitcnt lgkmcnt(0)
	v_mfma_f32_16x16x32_bf16 v[126:129], v[136:139], v[152:155], v[126:129]
	v_mfma_f32_16x16x32_bf16 v[122:125], v[144:147], v[152:155], v[122:125]
	v_mfma_f32_16x16x32_bf16 v[110:113], v[136:139], v[160:163], v[110:113]
	v_mfma_f32_16x16x32_bf16 v[106:109], v[144:147], v[160:163], v[106:109]
	v_mfma_f32_16x16x32_bf16 v[94:97], v[136:139], v[188:191], v[94:97]
	v_mfma_f32_16x16x32_bf16 v[90:93], v[144:147], v[188:191], v[90:93]
	v_mfma_f32_16x16x32_bf16 v[78:81], v[136:139], v[196:199], v[78:81]
	v_mfma_f32_16x16x32_bf16 v[74:77], v[144:147], v[196:199], v[74:77]
	v_mfma_f32_16x16x32_bf16 v[126:129], v[140:143], v[156:159], v[126:129]
	v_mfma_f32_16x16x32_bf16 v[122:125], v[148:151], v[156:159], v[122:125]
	v_mfma_f32_16x16x32_bf16 v[110:113], v[140:143], v[184:187], v[110:113]
	v_mfma_f32_16x16x32_bf16 v[106:109], v[148:151], v[184:187], v[106:109]
	v_mfma_f32_16x16x32_bf16 v[94:97], v[140:143], v[192:195], v[94:97]
	v_mfma_f32_16x16x32_bf16 v[90:93], v[148:151], v[192:195], v[90:93]
	v_mfma_f32_16x16x32_bf16 v[78:81], v[140:143], v[200:203], v[78:81]
	v_mfma_f32_16x16x32_bf16 v[74:77], v[148:151], v[200:203], v[74:77]
	s_barrier
	s_add_i32 s4, 0, 0x14000
	s_add_i32 s6, s6, s87
	s_mov_b32 m0, s6
	ds_read_b128 v[204:207], v245
	ds_read_b128 v[208:211], v245 offset:1024
	ds_read_b128 v[234:237], v245 offset:2048
	ds_read_b128 v[238:241], v245 offset:3072
	global_load_lds_dwordx4 v172, s[100:101]
	s_add_i32 m0, s6, 0x2000
	s_nop 0
	global_load_lds_dwordx4 v168, s[100:101]
	s_waitcnt lgkmcnt(0)
	s_barrier
	v_mfma_f32_16x16x32_bf16 v[118:121], v[204:207], v[152:155], v[118:121]
	v_mfma_f32_16x16x32_bf16 v[114:117], v[234:237], v[152:155], v[114:117]
	v_mfma_f32_16x16x32_bf16 v[102:105], v[204:207], v[160:163], v[102:105]
	v_mfma_f32_16x16x32_bf16 v[98:101], v[234:237], v[160:163], v[98:101]
	v_mfma_f32_16x16x32_bf16 v[86:89], v[204:207], v[188:191], v[86:89]
	v_mfma_f32_16x16x32_bf16 v[82:85], v[234:237], v[188:191], v[82:85]
	v_mfma_f32_16x16x32_bf16 v[70:73], v[204:207], v[196:199], v[70:73]
	v_mfma_f32_16x16x32_bf16 v[66:69], v[234:237], v[196:199], v[66:69]
	v_mfma_f32_16x16x32_bf16 v[118:121], v[208:211], v[156:159], v[118:121]
	v_mfma_f32_16x16x32_bf16 v[114:117], v[238:241], v[156:159], v[114:117]
	v_mfma_f32_16x16x32_bf16 v[102:105], v[208:211], v[184:187], v[102:105]
	v_mfma_f32_16x16x32_bf16 v[98:101], v[238:241], v[184:187], v[98:101]
	v_mfma_f32_16x16x32_bf16 v[86:89], v[208:211], v[192:195], v[86:89]
	v_mfma_f32_16x16x32_bf16 v[82:85], v[238:241], v[192:195], v[82:85]
	v_mfma_f32_16x16x32_bf16 v[70:73], v[208:211], v[200:203], v[70:73]
	v_mfma_f32_16x16x32_bf16 v[66:69], v[238:241], v[200:203], v[66:69]
	s_barrier
	s_mov_b32 m0, s2
	ds_read_b128 v[152:155], v233 offset:16384
	ds_read_b128 v[156:159], v233 offset:17408
	ds_read_b128 v[160:163], v233 offset:18432
	ds_read_b128 v[184:187], v233 offset:19456
	ds_read_b128 v[188:191], v233 offset:20480
	ds_read_b128 v[192:195], v233 offset:21504
	ds_read_b128 v[196:199], v233 offset:22528
	ds_read_b128 v[200:203], v233 offset:23552
	global_load_lds_dwordx4 v170, s[98:99]
	s_mov_b32 m0, s3
	s_nop 0
	global_load_lds_dwordx4 v166, s[98:99]
	s_waitcnt lgkmcnt(0)
	s_barrier
	v_mfma_f32_16x16x32_bf16 v[62:65], v[136:139], v[152:155], v[62:65]
	v_mfma_f32_16x16x32_bf16 v[58:61], v[144:147], v[152:155], v[58:61]
	v_mfma_f32_16x16x32_bf16 v[46:49], v[136:139], v[160:163], v[46:49]
	v_mfma_f32_16x16x32_bf16 v[42:45], v[144:147], v[160:163], v[42:45]
	v_mfma_f32_16x16x32_bf16 v[30:33], v[136:139], v[188:191], v[30:33]
	v_mfma_f32_16x16x32_bf16 v[26:29], v[144:147], v[188:191], v[26:29]
	v_mfma_f32_16x16x32_bf16 v[14:17], v[136:139], v[196:199], v[14:17]
	v_mfma_f32_16x16x32_bf16 v[10:13], v[144:147], v[196:199], v[10:13]
	v_mfma_f32_16x16x32_bf16 v[62:65], v[140:143], v[156:159], v[62:65]
	v_mfma_f32_16x16x32_bf16 v[58:61], v[148:151], v[156:159], v[58:61]
	v_mfma_f32_16x16x32_bf16 v[46:49], v[140:143], v[184:187], v[46:49]
	v_mfma_f32_16x16x32_bf16 v[42:45], v[148:151], v[184:187], v[42:45]
	v_mfma_f32_16x16x32_bf16 v[30:33], v[140:143], v[192:195], v[30:33]
	v_mfma_f32_16x16x32_bf16 v[26:29], v[148:151], v[192:195], v[26:29]
	v_mfma_f32_16x16x32_bf16 v[14:17], v[140:143], v[200:203], v[14:17]
	v_mfma_f32_16x16x32_bf16 v[10:13], v[148:151], v[200:203], v[10:13]
	s_barrier
	s_add_i32 s4, s4, s87
	s_mov_b32 m0, s4
	s_nop 0
	global_load_lds_dwordx4 v242, s[100:101]
	s_add_i32 m0, s4, 0x2000
	s_nop 0
	global_load_lds_dwordx4 v243, s[100:101]
	s_waitcnt vmcnt(6)
	s_barrier
	v_mfma_f32_16x16x32_bf16 v[54:57], v[204:207], v[152:155], v[54:57]
	v_mfma_f32_16x16x32_bf16 v[50:53], v[234:237], v[152:155], v[50:53]
	v_mfma_f32_16x16x32_bf16 v[38:41], v[204:207], v[160:163], v[38:41]
	v_mfma_f32_16x16x32_bf16 v[34:37], v[234:237], v[160:163], v[34:37]
	v_mfma_f32_16x16x32_bf16 v[22:25], v[204:207], v[188:191], v[22:25]
	v_mfma_f32_16x16x32_bf16 v[18:21], v[234:237], v[188:191], v[18:21]
	v_mfma_f32_16x16x32_bf16 v[6:9], v[204:207], v[196:199], v[6:9]
	v_mfma_f32_16x16x32_bf16 v[2:5], v[234:237], v[196:199], v[2:5]
	v_mfma_f32_16x16x32_bf16 v[54:57], v[208:211], v[156:159], v[54:57]
	v_mfma_f32_16x16x32_bf16 v[50:53], v[238:241], v[156:159], v[50:53]
	v_mfma_f32_16x16x32_bf16 v[38:41], v[208:211], v[184:187], v[38:41]
	v_mfma_f32_16x16x32_bf16 v[34:37], v[238:241], v[184:187], v[34:37]
	v_mfma_f32_16x16x32_bf16 v[22:25], v[208:211], v[192:195], v[22:25]
	v_mfma_f32_16x16x32_bf16 v[18:21], v[238:241], v[192:195], v[18:21]
	v_mfma_f32_16x16x32_bf16 v[6:9], v[208:211], v[200:203], v[6:9]
	v_mfma_f32_16x16x32_bf16 v[2:5], v[238:241], v[200:203], v[2:5]
	s_barrier
; #define PG8_STAGE(bufoff, gbase, voff) do { _Pragma("unroll") for (int _i = 0; _i < 2; ++_i) \
;         __builtin_amdgcn_global_load_lds((const unsigned*)((const char*)(gbase) + (voff)[_i]), (LAS unsigned*)(lds + (bufoff) + ldsw + _i * 8192), 16, 0, 0); } while (0)
; #define PG8_LDA(dst, b, h) do { _Pragma("unroll") for (int m = 0; m < 4; ++m) _Pragma("unroll") for (int k = 0; k < 2; ++k) dst[m][k] = *(const LAS bf16x8*)(lds + PG8_SA(b, h) + aoff + m * 2048 + k * 1024); } while (0)
; #define PG8_LDB(dst, b, h) do { _Pragma("unroll") for (int n = 0; n < 2; ++n) _Pragma("unroll") for (int k = 0; k < 2; ++k) dst[n][k] = *(const LAS bf16x8*)(lds + PG8_SB(b, h) + boff + n * 2048 + k * 1024); } while (0)
; #define PG8_MMA(ai, bj, At, Bt) do { __builtin_amdgcn_s_setprio(1); _Pragma("unroll") for (int m = 0; m < 4; ++m) _Pragma("unroll") for (int n = 0; n < 2; ++n) _Pragma("unroll") for (int k = 0; k < 2; ++k) \
;         acc[ai][bj][m][n] = __builtin_amdgcn_mfma_f32_16x16x32_bf16(Bt[n][k], At[m][k], acc[ai][bj][m][n], 0, 0, 0); __builtin_amdgcn_s_setprio(0); } while (0)
; #define PG8_WAIT_V(n) asm volatile("s_waitcnt vmcnt(" #n ")" ::: "memory")
; #define PG8_WAIT_L(n) asm volatile("s_waitcnt lgkmcnt(" #n ")" ::: "memory")
; #define PG8_BAR __builtin_amdgcn_s_barrier()
; #define PG8_SCHED __builtin_amdgcn_sched_barrier(0)
; __device__ __forceinline__ void gemm_phase(LAS unsigned char* lds, const GemmD& g) {
;     ...
;             PG8_LDB(B0, 1, 0); PG8_SCHED; PG8_LDA(At, 1, 0); PG8_STAGE(PG8_SA(0, 1), a2 + hstep, voffA);
;             PG8_WAIT_L(8); PG8_BAR; PG8_WAIT_L(0); PG8_MMA(0, 0, At, B0); PG8_BAR; PG8_SCHED;
;             PG8_LDB(B1, 1, 1); PG8_STAGE(PG8_SB(1, 0), b3, voffB);
;             PG8_BAR; PG8_WAIT_L(0); PG8_MMA(0, 1, At, B1); PG8_BAR;
;             PG8_LDA(At, 1, 1); PG8_STAGE(PG8_SA(1, 0), a3, voffA);
;             PG8_BAR; PG8_WAIT_L(0); PG8_MMA(1, 0, At, B0); PG8_BAR; PG8_SCHED;
;             PG8_STAGE(PG8_SB(1, 1), b3 + hstep, voffB);
;             PG8_WAIT_V(6); PG8_BAR; PG8_MMA(1, 1, At, B1); PG8_BAR;
;         }
	s_add_i32 s4, 0, 0x18000
	ds_read_b128 v[136:139], v246
	ds_read_b128 v[140:143], v246 offset:1024
	ds_read_b128 v[144:147], v246 offset:2048
	ds_read_b128 v[148:151], v246 offset:3072
	s_mov_b32 m0, s64
	ds_read_b128 v[152:155], v233 offset:32768
	ds_read_b128 v[156:159], v233 offset:33792
	ds_read_b128 v[160:163], v233 offset:34816
	ds_read_b128 v[184:187], v233 offset:35840
	ds_read_b128 v[188:191], v233 offset:36864
	ds_read_b128 v[192:195], v233 offset:37888
	ds_read_b128 v[196:199], v233 offset:38912
	ds_read_b128 v[200:203], v233 offset:39936
	global_load_lds_dwordx4 v174, s[98:99]
	s_mov_b32 m0, s65
	s_nop 0
	global_load_lds_dwordx4 v176, s[98:99]
	s_waitcnt lgkmcnt(8)
	s_barrier
	s_waitcnt lgkmcnt(0)
	v_mfma_f32_16x16x32_bf16 v[126:129], v[136:139], v[152:155], v[126:129]
	v_mfma_f32_16x16x32_bf16 v[122:125], v[144:147], v[152:155], v[122:125]
	v_mfma_f32_16x16x32_bf16 v[110:113], v[136:139], v[160:163], v[110:113]
	v_mfma_f32_16x16x32_bf16 v[106:109], v[144:147], v[160:163], v[106:109]
	v_mfma_f32_16x16x32_bf16 v[94:97], v[136:139], v[188:191], v[94:97]
	v_mfma_f32_16x16x32_bf16 v[90:93], v[144:147], v[188:191], v[90:93]
	v_mfma_f32_16x16x32_bf16 v[78:81], v[136:139], v[196:199], v[78:81]
	v_mfma_f32_16x16x32_bf16 v[74:77], v[144:147], v[196:199], v[74:77]
	v_mfma_f32_16x16x32_bf16 v[126:129], v[140:143], v[156:159], v[126:129]
	v_mfma_f32_16x16x32_bf16 v[122:125], v[148:151], v[156:159], v[122:125]
	v_mfma_f32_16x16x32_bf16 v[110:113], v[140:143], v[184:187], v[110:113]
	v_mfma_f32_16x16x32_bf16 v[106:109], v[148:151], v[184:187], v[106:109]
	v_mfma_f32_16x16x32_bf16 v[94:97], v[140:143], v[192:195], v[94:97]
	v_mfma_f32_16x16x32_bf16 v[90:93], v[148:151], v[192:195], v[90:93]
	v_mfma_f32_16x16x32_bf16 v[78:81], v[140:143], v[200:203], v[78:81]
	v_mfma_f32_16x16x32_bf16 v[74:77], v[148:151], v[200:203], v[74:77]
	s_barrier
	s_add_i32 s6, 0, 0x1c000
	s_add_i32 s4, s4, s87
	ds_read_b128 v[204:207], v247
	ds_read_b128 v[208:211], v247 offset:1024
	ds_read_b128 v[234:237], v247 offset:2048
	ds_read_b128 v[238:241], v247 offset:3072
	s_add_u32 s100, s100, 0x80
	s_addc_u32 s101, s101, 0
	s_mov_b32 m0, s4
	s_nop 0
	global_load_lds_dwordx4 v172, s[100:101]
	s_add_i32 m0, s4, 0x2000
	s_nop 0
	global_load_lds_dwordx4 v168, s[100:101]
	s_waitcnt lgkmcnt(0)
	s_barrier
	v_mfma_f32_16x16x32_bf16 v[118:121], v[204:207], v[152:155], v[118:121]
	v_mfma_f32_16x16x32_bf16 v[114:117], v[234:237], v[152:155], v[114:117]
	v_mfma_f32_16x16x32_bf16 v[102:105], v[204:207], v[160:163], v[102:105]
	v_mfma_f32_16x16x32_bf16 v[98:101], v[234:237], v[160:163], v[98:101]
	v_mfma_f32_16x16x32_bf16 v[86:89], v[204:207], v[188:191], v[86:89]
	v_mfma_f32_16x16x32_bf16 v[82:85], v[234:237], v[188:191], v[82:85]
	v_mfma_f32_16x16x32_bf16 v[70:73], v[204:207], v[196:199], v[70:73]
	v_mfma_f32_16x16x32_bf16 v[66:69], v[234:237], v[196:199], v[66:69]
	v_mfma_f32_16x16x32_bf16 v[118:121], v[208:211], v[156:159], v[118:121]
	v_mfma_f32_16x16x32_bf16 v[114:117], v[238:241], v[156:159], v[114:117]
	v_mfma_f32_16x16x32_bf16 v[102:105], v[208:211], v[184:187], v[102:105]
	v_mfma_f32_16x16x32_bf16 v[98:101], v[238:241], v[184:187], v[98:101]
	v_mfma_f32_16x16x32_bf16 v[86:89], v[208:211], v[192:195], v[86:89]
	v_mfma_f32_16x16x32_bf16 v[82:85], v[238:241], v[192:195], v[82:85]
	v_mfma_f32_16x16x32_bf16 v[70:73], v[208:211], v[200:203], v[70:73]
	v_mfma_f32_16x16x32_bf16 v[66:69], v[238:241], v[200:203], v[66:69]
	s_barrier
	s_mov_b32 m0, s28
	s_add_u32 s98, s98, 0x80
	s_addc_u32 s99, s99, 0
	ds_read_b128 v[152:155], v233 offset:49152
	ds_read_b128 v[156:159], v233 offset:50176
	ds_read_b128 v[160:163], v233 offset:51200
	ds_read_b128 v[184:187], v233 offset:52224
	ds_read_b128 v[188:191], v233 offset:53248
	ds_read_b128 v[192:195], v233 offset:54272
	ds_read_b128 v[196:199], v233 offset:55296
	ds_read_b128 v[200:203], v233 offset:56320
	global_load_lds_dwordx4 v170, s[98:99]
	s_mov_b32 m0, s29
	s_nop 0
	global_load_lds_dwordx4 v166, s[98:99]
	s_waitcnt lgkmcnt(0)
	s_barrier
	v_mfma_f32_16x16x32_bf16 v[62:65], v[136:139], v[152:155], v[62:65]
	v_mfma_f32_16x16x32_bf16 v[58:61], v[144:147], v[152:155], v[58:61]
	v_mfma_f32_16x16x32_bf16 v[46:49], v[136:139], v[160:163], v[46:49]
	v_mfma_f32_16x16x32_bf16 v[42:45], v[144:147], v[160:163], v[42:45]
	v_mfma_f32_16x16x32_bf16 v[30:33], v[136:139], v[188:191], v[30:33]
	v_mfma_f32_16x16x32_bf16 v[26:29], v[144:147], v[188:191], v[26:29]
	v_mfma_f32_16x16x32_bf16 v[14:17], v[136:139], v[196:199], v[14:17]
	v_mfma_f32_16x16x32_bf16 v[10:13], v[144:147], v[196:199], v[10:13]
	v_mfma_f32_16x16x32_bf16 v[62:65], v[140:143], v[156:159], v[62:65]
	v_mfma_f32_16x16x32_bf16 v[58:61], v[148:151], v[156:159], v[58:61]
	v_mfma_f32_16x16x32_bf16 v[46:49], v[140:143], v[184:187], v[46:49]
	v_mfma_f32_16x16x32_bf16 v[42:45], v[148:151], v[184:187], v[42:45]
	v_mfma_f32_16x16x32_bf16 v[30:33], v[140:143], v[192:195], v[30:33]
	v_mfma_f32_16x16x32_bf16 v[26:29], v[148:151], v[192:195], v[26:29]
	v_mfma_f32_16x16x32_bf16 v[14:17], v[140:143], v[200:203], v[14:17]
	v_mfma_f32_16x16x32_bf16 v[10:13], v[148:151], v[200:203], v[10:13]
	s_barrier
	s_add_i32 s4, s6, s87
	s_mov_b32 m0, s4
	s_nop 0
	global_load_lds_dwordx4 v242, s[100:101]
	s_add_i32 m0, s4, 0x2000
	s_nop 0
	global_load_lds_dwordx4 v243, s[100:101]
	s_add_u32 s100, s100, 0x80
	s_addc_u32 s101, s101, 0
	s_mov_b32 s4, s5
	s_waitcnt vmcnt(6)
	s_barrier
	v_mfma_f32_16x16x32_bf16 v[54:57], v[204:207], v[152:155], v[54:57]
	v_mfma_f32_16x16x32_bf16 v[50:53], v[234:237], v[152:155], v[50:53]
	v_mfma_f32_16x16x32_bf16 v[38:41], v[204:207], v[160:163], v[38:41]
	v_mfma_f32_16x16x32_bf16 v[34:37], v[234:237], v[160:163], v[34:37]
	v_mfma_f32_16x16x32_bf16 v[22:25], v[204:207], v[188:191], v[22:25]
	v_mfma_f32_16x16x32_bf16 v[18:21], v[234:237], v[188:191], v[18:21]
	v_mfma_f32_16x16x32_bf16 v[6:9], v[204:207], v[196:199], v[6:9]
	v_mfma_f32_16x16x32_bf16 v[2:5], v[234:237], v[196:199], v[2:5]
	v_mfma_f32_16x16x32_bf16 v[54:57], v[208:211], v[156:159], v[54:57]
	v_mfma_f32_16x16x32_bf16 v[50:53], v[238:241], v[156:159], v[50:53]
	v_mfma_f32_16x16x32_bf16 v[38:41], v[208:211], v[184:187], v[38:41]
	v_mfma_f32_16x16x32_bf16 v[34:37], v[238:241], v[184:187], v[34:37]
	v_mfma_f32_16x16x32_bf16 v[22:25], v[208:211], v[192:195], v[22:25]
	v_mfma_f32_16x16x32_bf16 v[18:21], v[238:241], v[192:195], v[18:21]
	v_mfma_f32_16x16x32_bf16 v[6:9], v[208:211], v[200:203], v[6:9]
	v_mfma_f32_16x16x32_bf16 v[2:5], v[238:241], v[200:203], v[2:5]
	s_barrier
	s_cbranch_vccz .LBB0_145
	v_lshl_add_u32 v184, s56, 8, v228
	s_cmp_lt_i32 s66, 0
	s_mov_b64 s[4:5], -1
	s_cbranch_scc0 .LBB0_704
